# one static s_setprio 1 for waves 0-3 replacing the per-cluster priority flips in both K-loops, on top of LN apply with prefetched row statistics
# baseline (speedup 1.0000x reference)
; #define LAS __attribute__((address_space(3)))
; __device__ __forceinline__ int lane_now() { int l; asm volatile("v_mbcnt_lo_u32_b32 %0, -1, 0\n\tv_mbcnt_hi_u32_b32 %0, -1, %0" : "=v"(l)); return l; }
; template <bool F8 = false, class Sched, class Epi>
; __device__ __forceinline__ void gemm_phase(LAS unsigned char* lds, const Sched& S, const Epi& E) {
;     int tid = S.wv * 64 + lane_now();
;     const int wid = S.wv, wr = wid >> 2, wc = wid & 3;
;     ...
;     const size_t kstep = (size_t)(BK * 2);
;     const unsigned ldsw = (unsigned)wid * 1024u;
;     int aoff, boff; { const int l0 = tid & 63; aoff = lds_byte(wr * 64 + (l0 & 15), (l0 >> 4) * 8); boff = lds_byte(wc * 32 + (l0 & 15), (l0 >> 4) * 8); }
; __global__ void __launch_bounds__(NTHREADS, 2) mk_fwd(Args args) {
;     ...
;     const int tid0 = threadIdx.x, lane0 = tid0 & 63, wave0 = __builtin_amdgcn_readfirstlane(tid0 >> 6);
;     const int G = gridDim.x, bx = blockIdx.x;
;     const int vcu = (G % 8 == 0) ? (bx % 8) * (G / 8) + bx / 8 : bx;
;     const int NGW = G * NWAVES;
;     const int NGT = G * NTHREADS;
;     unsigned char* ws = args.ws; float* out = args.out;
;     for (int u = tid0; u < (LDS_BYTES - LDSCTL_OFF) / 4; u += NTHREADS) ((LAS unsigned*)(lds + LDSCTL_OFF))[u] = 0u;
;     __syncthreads();
;     XcdBarrier bar = xcd_barrier_post((unsigned*)(ws + WS_CTL) + CW_BAR, MISC + 8, wave0);
;     ...
;     f16* H16 = (f16*)(ws + WS_H16);
;     constexpr int NSTEPS = 1 + 6 * DEPTH;
;     for (int step = 0; step < NSTEPS; ++step) {
;         const int layer = step == 0 ? 0 : (step - 1) / 6, s6 = step == 0 ? -1 : (step - 1) % 6;
;         const int st = s6 < 0 ? 0 : (s6 < 4 ? s6 + 1 : (s6 == 4 ? 6 : 8));
;         int tid = wave0 * 64 + lane_now();
;         int lane = tid & 63, gt = vcu * NTHREADS + tid;
;         int wave = wave0; asm volatile("" : "+s"(wave));
;         const int gw = vcu * NWAVES + wave;
.LBB0_13:
	s_or_b64 exec, exec, s[0:1]
	s_lshl_b32 s78, s47, 9
	s_lshl_b32 s64, s47, 3
	s_lshr_b32 s60, s10, 6
	s_add_u32 s18, s54, 0x2400000
	v_readlane_b32 s46, v251, 3
	s_addc_u32 s19, s55, 0
	s_lshl_b32 s0, s46, 9
	s_lshr_b32 s14, s10, 8
	v_writelane_b32 v251, s0, 6
	s_lshl_b32 s0, s14, 13
	v_writelane_b32 v251, s0, 7
	s_lshl_b32 s0, s60, 5
	s_and_b32 s92, s0, 0x60
	v_writelane_b32 v251, s0, 8
	s_lshl_b32 s0, s92, 7
	v_writelane_b32 v251, s0, 9
	s_and_b32 s94, s10, 0xffffffc0
	s_lshl_b32 s16, s46, 3
	s_lshl_b32 s49, s60, 10
	s_lshl_b32 s48, s14, 6
	v_readlane_b32 s13, v251, 2
	s_cmpk_gt_i32 s13, 0xff
	s_cselect_b64 s[0:1], -1, 0
	v_writelane_b32 v251, s0, 10
	s_cmpk_lt_i32 s13, 0x100
	s_mov_b32 s97, 0
	v_writelane_b32 v251, s1, 11
	s_cselect_b64 s[0:1], -1, 0
	s_ashr_i32 s2, s13, 31
	s_lshr_b32 s2, s2, 29
	s_add_i32 s3, s13, s2
	s_ashr_i32 s2, s3, 3
	s_and_b32 s3, s3, -8
	s_sub_i32 s3, s13, s3
	s_lshl_b32 s4, s3, 5
	s_add_u32 s44, s54, 0x13400000
	s_addc_u32 s45, s55, 0
	s_add_u32 s20, s54, 0x14600000
	s_addc_u32 s21, s55, 0
	s_add_u32 s62, s54, 0x14400000
	s_addc_u32 s63, s55, 0
	s_cmp_eq_u32 s14, 1
	s_cselect_b64 s[58:59], -1, 0
	s_cmpk_lt_u32 s10, 0x100
	s_cselect_b64 s[8:9], -1, 0
	v_writelane_b32 v251, s8, 12
	s_cmpk_gt_u32 s10, 0xff
	s_mul_i32 s6, s3, 33
	v_writelane_b32 v251, s9, 13
	s_cselect_b64 s[8:9], -1, 0
	v_writelane_b32 v251, s8, 14
	s_cmp_lt_u32 s10, 64
	v_cndmask_b32_e64 v218, 0, 1, s[0:1]
	v_writelane_b32 v251, s9, 15
	s_cselect_b64 s[8:9], -1, 0
	v_writelane_b32 v251, s8, 16
	s_mul_i32 s87, s47, 24
	v_mov_b32_e32 v33, 0
	v_writelane_b32 v251, s9, 17
	s_add_u32 s8, s54, 0x4200
	s_addc_u32 s9, s55, 0
	v_writelane_b32 v251, s8, 18
	s_add_u32 s5, s54, 0x10000
	v_mov_b32_e32 v220, 0x7b
	v_writelane_b32 v251, s9, 19
	v_writelane_b32 v251, s5, 20
	s_addc_u32 s5, s55, 0
	s_add_u32 s22, s54, 0x6c00000
	s_addc_u32 s23, s55, 0
	s_add_u32 s8, s54, 0xc400000
	v_writelane_b32 v251, s5, 21
	s_addc_u32 s9, s55, 0
	v_writelane_b32 v251, s8, 22
	v_mov_b32_e32 v221, 0x7f
	v_mov_b32_e32 v222, 1
	v_writelane_b32 v251, s9, 23
	s_add_u32 s8, s54, 0xc560000
	s_addc_u32 s9, s55, 0
	v_writelane_b32 v251, s8, 24
	v_mov_b32_e32 v223, 0x3727c5ac
	v_mov_b32_e32 v224, 0x260
	v_writelane_b32 v251, s9, 25
	s_add_u32 s8, s54, 0xc6c0000
	s_addc_u32 s9, s55, 0
	v_writelane_b32 v251, s8, 26
	s_bfe_u32 s11, s10, 0x20006
	s_lshl_b32 s5, s11, 5
	v_writelane_b32 v251, s9, 27
	v_writelane_b32 v251, s5, 28
	s_lshl_b32 s5, s11, 12
	s_cmpk_gt_i32 s13, 0x7f
	v_writelane_b32 v251, s5, 29
	s_cselect_b64 s[8:9], -1, 0
	v_writelane_b32 v251, s8, 30
	s_lshl_b32 s5, s3, 4
	s_cmp_lt_i32 s3, 0
	v_writelane_b32 v251, s9, 31
	s_movk_i32 s8, 0xb1
	s_cselect_b32 s8, s8, 0xb0
	s_mul_i32 s8, s8, s3
	s_mul_i32 s3, s3, 17
	s_cselect_b32 s12, s6, s4
	s_cselect_b32 s3, s3, s5
	s_add_i32 s8, s8, s2
	s_mul_hi_i32 s4, s8, 0x2e8ba2e9
	s_lshr_b32 s5, s4, 31
	s_ashr_i32 s4, s4, 5
	s_add_i32 s4, s4, s5
	s_mul_i32 s5, s4, 0xb0
	s_sub_i32 s5, s8, s5
	s_lshl_b32 s6, s4, 3
	s_bfe_u32 s4, s5, 0x3001c
	s_add_i32 s8, s5, s4
	s_sext_i32_i16 s9, s8
	s_and_b32 s8, s8, 0xfff8
	s_sub_i32 s5, s5, s8
	s_sext_i32_i16 s5, s5
	s_add_i32 s8, s6, s5
	s_lshr_b32 s4, s9, 3
	s_ashr_i32 s5, s9, 3
	s_ashr_i32 s9, s8, 31
	v_writelane_b32 v251, s5, 32
	s_mov_b32 s6, s8
	s_lshl_b64 s[8:9], s[8:9], 19
	v_writelane_b32 v251, s6, 33
	s_add_u32 s8, s18, s8
	s_addc_u32 s9, s19, s9
	v_writelane_b32 v251, s7, 34
	v_writelane_b32 v251, s8, 35
	v_mov_b32_e32 v233, 0x5800
	v_mov_b32_e32 v250, 0xff
	v_writelane_b32 v251, s9, 36
	s_add_u32 s8, s54, 0x1000000
	s_addc_u32 s9, s55, 0
	s_bfe_i64 s[4:5], s[4:5], 0x100000
	s_lshl_b64 s[4:5], s[4:5], 18
	s_add_u32 s4, s8, s4
	v_writelane_b32 v251, s8, 37
	s_addc_u32 s5, s9, s5
	s_bfe_u32 s6, s13, 0x50003
	v_writelane_b32 v251, s9, 38
	v_writelane_b32 v251, s4, 39
	s_lshr_b32 s8, s13, 3
	v_mov_b32_e32 v228, 0xb9d0
	v_writelane_b32 v251, s5, 40
	s_lshl_b32 s4, s13, 5
	s_and_b32 s4, s4, 0xe0
	s_add_i32 s4, s4, s8
	s_lshr_b32 s4, s4, 2
	s_and_b32 s4, s4, 0x7fffff8
	s_sub_i32 s5, 64, s4
	s_min_i32 s5, s5, 8
	s_add_u32 s24, s54, 0x4400000
	s_addc_u32 s25, s55, 0
	s_add_u32 s26, s54, 0x2300000
	s_addc_u32 s27, s55, 0
	s_add_u32 s28, s54, 0x10c00000
	s_addc_u32 s29, s55, 0
	s_add_u32 s30, s54, 0xe00000
	s_addc_u32 s31, s55, 0
	s_add_u32 s34, s54, 0xec00000
	s_addc_u32 s35, s55, 0
	s_add_u32 s36, s54, 0xc00000
	s_addc_u32 s37, s55, 0
	s_cmpk_lt_i32 s13, 0x80
	s_cselect_b64 s[38:39], -1, 0
	s_lshl_b32 s9, s13, 4
	s_and_b32 s8, s8, 30
	s_and_b32 s9, s9, 0x70
	s_xor_b32 s8, s8, 16
	v_writelane_b32 v251, s38, 41
	s_add_i32 s8, s8, s9
	s_bfe_u32 s9, s13, 0x10003
	v_writelane_b32 v251, s39, 42
	s_lshr_b32 s13, s8, 1
	v_writelane_b32 v251, s13, 43
	v_writelane_b32 v251, s9, 44
	s_lshl_b32 s9, s9, 19
	s_add_u32 s9, s54, s9
	s_addc_u32 s13, s55, 0
	s_add_u32 s38, s9, 0x600000
	s_addc_u32 s39, s13, 0
	s_lshl_b32 s8, s8, 18
	v_writelane_b32 v251, s38, 45
	s_add_u32 s8, s18, s8
	s_addc_u32 s9, s19, 0
	v_writelane_b32 v251, s39, 46
	v_writelane_b32 v251, s8, 47
	s_add_u32 s38, s54, 0x400000
	s_addc_u32 s39, s55, 0
	v_writelane_b32 v251, s9, 48
	s_lshl_b32 s8, s11, 7
	s_add_i32 s8, s8, 0
	s_add_i32 s9, s8, 0x20400
	s_lshl_b32 s8, s14, 10
	v_writelane_b32 v251, s8, 49
	s_add_i32 s13, s9, s8
	s_add_i32 s8, s14, 2
	s_lshl_b32 s15, s8, 10
	v_writelane_b32 v251, s9, 50
	s_add_i32 s9, s9, s15
	s_cmpk_lt_u32 s10, 0x300
	v_writelane_b32 v251, s15, 51
	s_cselect_b64 s[40:41], -1, 0
	v_writelane_b32 v251, s40, 52
	s_add_i32 s10, s13, 0xfffffe00
	s_cmp_eq_u32 s14, 3
	v_writelane_b32 v251, s41, 53
	v_writelane_b32 v251, s13, 54
	v_writelane_b32 v251, s10, 55
	v_writelane_b32 v251, s14, 56
	s_cselect_b64 s[14:15], -1, 0
; #define LAS __attribute__((address_space(3)))
; __device__ __forceinline__ int lane_now() { int l; asm volatile("v_mbcnt_lo_u32_b32 %0, -1, 0\n\tv_mbcnt_hi_u32_b32 %0, -1, %0" : "=v"(l)); return l; }
; __global__ void __launch_bounds__(NTHREADS, 2) mk_fwd(Args args) {
;     ...
;     const int tid0 = threadIdx.x, lane0 = tid0 & 63, wave0 = __builtin_amdgcn_readfirstlane(tid0 >> 6);
;     const int G = gridDim.x, bx = blockIdx.x;
;     const int vcu = (G % 8 == 0) ? (bx % 8) * (G / 8) + bx / 8 : bx;
;     const int NGW = G * NWAVES;
;     const int NGT = G * NTHREADS;
;     unsigned char* ws = args.ws; float* out = args.out;
;     for (int u = tid0; u < (LDS_BYTES - LDSCTL_OFF) / 4; u += NTHREADS) ((LAS unsigned*)(lds + LDSCTL_OFF))[u] = 0u;
;     __syncthreads();
;     XcdBarrier bar = xcd_barrier_post((unsigned*)(ws + WS_CTL) + CW_BAR, MISC + 8, wave0);
;     ...
;     f16* H16 = (f16*)(ws + WS_H16);
;     constexpr int NSTEPS = 1 + 6 * DEPTH;
;     for (int step = 0; step < NSTEPS; ++step) {
;         const int layer = step == 0 ? 0 : (step - 1) / 6, s6 = step == 0 ? -1 : (step - 1) % 6;
;         const int st = s6 < 0 ? 0 : (s6 < 4 ? s6 + 1 : (s6 == 4 ? 6 : 8));
;         int tid = wave0 * 64 + lane_now();
;         int lane = tid & 63, gt = vcu * NTHREADS + tid;
;         int wave = wave0; asm volatile("" : "+s"(wave));
;         const int gw = vcu * NWAVES + wave;
;         if (st == 1 || st == 3) {
;             const Sched S8{st == 1 ? PH_AQ : PH_A8, bx, G, ws, layer & 1, wave0}; const EpiGate EG{ws, args.in[5] + (size_t)layer * NPROJ, 0};
;             pg8::gemm_phase<true>(lds, S8, EG);
;         }
;         if (st == 2 || st == 3 || st == 4) xcd_barrier_wait(bar);
;         if (st == 1 || st == 3 || st == 4 || st == 6 || st == 8) {
;             const int ph = st == 1 ? PH_A : (st == 3 ? PH_C : (st == 4 ? PH_D : (st == 6 ? PH_E : PH_F)));
;             const Epi E{ws, out, args.in[5] + (size_t)layer * NPROJ, args.in[st == 4 ? 12 : 20] + (size_t)layer * DM, args.in[st == 4 ? 13 : 21] + (size_t)layer * DM,
;                         (unsigned*)(ws + WS_CTL) + CW_SEAM + (2 * layer + (st == 4 ? 0 : 1)) * SEAM_BANK, args.in[15] + (size_t)layer * 3 * DFF, args.in[16] + (size_t)layer * DFF, 0, (layer == DEPTH - 1 && st == 8) ? 1 : 0, st == 8 ? 1 : 0};
	v_writelane_b32 v251, s14, 57
	v_mov_b64_e32 v[230:231], 0x1e8481
	v_mov_b32_e32 v229, 0x7fc00000
	v_writelane_b32 v251, s15, 58
	v_writelane_b32 v251, s9, 59
	s_addk_i32 s9, 0xfe00
	s_cmp_eq_u32 s8, 3
	v_writelane_b32 v251, s9, 60
	s_cselect_b64 s[8:9], -1, 0
	v_writelane_b32 v251, s8, 61
	v_mov_b32_e32 v225, 0x200
	v_mov_b32_e32 v232, 0xfb53
	v_writelane_b32 v251, s9, 62
	s_add_u32 s8, s54, 0xfc00000
	s_addc_u32 s9, s55, 0
	v_writelane_b32 v251, s8, 63
	s_movk_i32 s89, 0x800
	v_readlane_b32 s14, v251, 4
	v_writelane_b32 v252, s9, 0
	s_add_u32 s8, s54, 0xd00000
	s_addc_u32 s9, s55, 0
	v_writelane_b32 v252, s8, 1
	v_readlane_b32 s15, v251, 5
	s_mov_b32 s90, 0
	v_writelane_b32 v252, s9, 2
	s_add_u32 s8, s54, 0x4c00000
	s_addc_u32 s9, s55, 0
	v_writelane_b32 v252, s8, 3
	s_mov_b64 s[76:77], 0x30080
	s_nop 0
	v_writelane_b32 v252, s9, 4
	s_add_u32 s8, s54, 0xac00000
	s_addc_u32 s9, s55, 0
	v_writelane_b32 v252, s8, 5
	s_nop 1
	v_writelane_b32 v252, s9, 6
	s_add_u32 s8, s54, 0x9c00000
	s_addc_u32 s9, s55, 0
	v_writelane_b32 v252, s8, 7
	s_nop 1
	v_writelane_b32 v252, s9, 8
	s_add_u32 s8, s54, 0x8c00000
	s_addc_u32 s9, s55, 0
	v_writelane_b32 v252, s8, 9
	s_nop 1
	v_writelane_b32 v252, s9, 10
	s_add_u32 s8, s54, 0x7c00000
	s_addc_u32 s9, s55, 0
	v_writelane_b32 v252, s8, 11
	s_nop 1
	v_writelane_b32 v252, s9, 12
	s_lshl_b32 s8, s11, 3
	s_add_i32 s8, s8, 0
	v_writelane_b32 v252, s8, 13
	s_add_u32 s8, s54, 0x100000
	s_addc_u32 s9, s55, 0
	v_writelane_b32 v252, s8, 14
	s_ashr_i32 s79, s78, 31
	s_lshl_b32 s40, s47, 5
	v_writelane_b32 v252, s9, 15
	s_lshl_b64 s[8:9], s[78:79], 2
	v_writelane_b32 v252, s8, 16
	s_cmpk_lt_i32 s46, 0x100
	s_nop 0
	v_writelane_b32 v252, s9, 17
	s_cselect_b64 s[8:9], -1, 0
	s_lshl_b32 s7, s7, 2
	v_writelane_b32 v252, s8, 18
	s_add_u32 s7, s14, s7
	s_nop 0
	v_writelane_b32 v252, s9, 19
	s_addc_u32 s8, s15, 0
	s_add_u32 s10, s7, 0x1400
	s_addc_u32 s11, s8, 0
	s_lshl_b32 s7, s33, 2
	s_add_u32 s7, s14, s7
	v_writelane_b32 v252, s10, 20
	s_addc_u32 s8, s15, 0
	s_nop 0
	v_writelane_b32 v252, s11, 21
	s_add_u32 s10, s7, 0x3400
	s_addc_u32 s11, s8, 0
	v_writelane_b32 v252, s10, 22
	s_cmpk_eq_i32 s47, 0x100
	s_cselect_b64 s[8:9], -1, 0
	v_writelane_b32 v252, s11, 23
	v_writelane_b32 v252, s8, 24
	s_add_i32 s7, s12, s2
	s_nop 0
	v_writelane_b32 v252, s9, 25
	s_ashr_i32 s8, s7, 31
	s_lshr_b32 s8, s8, 27
	s_add_i32 s8, s7, s8
	s_and_b32 s9, s8, 0xffffffe0
	s_sub_i32 s7, s7, s9
	s_ashr_i32 s8, s8, 5
	s_lshl_b32 s14, s8, 3
	s_bfe_i32 s8, s7, 0x80000
	s_bfe_u32 s8, s8, 0x3000c
	s_add_i32 s8, s7, s8
	s_bfe_i32 s9, s8, 0x80000
	s_and_b32 s8, s8, 0xf8
	s_sub_i32 s8, s7, s8
	s_sext_i32_i8 s8, s8
	s_add_i32 s42, s14, s8
	s_sext_i32_i16 s9, s9
	s_ashr_i32 s43, s42, 31
	s_ashr_i32 s17, s9, 3
	s_lshr_b32 s8, s9, 3
	s_lshl_b64 s[50:51], s[42:43], 18
	s_add_u32 s10, s44, s50
	v_writelane_b32 v252, s44, 26
	s_addc_u32 s11, s45, s51
	s_nop 0
	v_writelane_b32 v252, s45, 27
	v_writelane_b32 v252, s10, 28
	s_nop 1
	v_writelane_b32 v252, s11, 29
	s_bfe_i64 s[10:11], s[8:9], 0x100000
	s_lshl_b64 s[56:57], s[10:11], 18
	s_add_u32 s12, s20, s56
	v_writelane_b32 v252, s20, 30
	s_addc_u32 s13, s21, s57
	s_cmp_gt_i32 s7, 15
	v_writelane_b32 v252, s21, 31
	v_writelane_b32 v252, s12, 32
	s_nop 1
	v_writelane_b32 v252, s13, 33
	s_cselect_b64 s[12:13], -1, 0
	v_cndmask_b32_e64 v0, 0, 1, s[12:13]
	s_add_u32 s12, s62, s56
	v_writelane_b32 v252, s62, 34
	s_addc_u32 s13, s63, s57
	s_add_i32 s8, s8, 8
	v_writelane_b32 v252, s63, 35
	v_writelane_b32 v252, s12, 36
	s_and_b32 s8, s8, 0xff
	s_mov_b32 s62, 0x437f0000
	v_writelane_b32 v252, s13, 37
	v_writelane_b32 v252, s8, 38
	s_sub_i32 s8, 64, s14
	s_min_i32 s12, s8, 8
	s_add_u32 s8, s34, s50
	v_writelane_b32 v252, s34, 39
	s_nop 1
	v_writelane_b32 v252, s35, 40
	v_writelane_b32 v252, s50, 41
	s_addc_u32 s9, s35, s51
	s_nop 0
	v_writelane_b32 v252, s51, 42
	v_writelane_b32 v252, s8, 43
	s_movk_i32 s51, 0x3dc5
	s_nop 0
	v_writelane_b32 v252, s9, 44
	s_add_u32 s8, s36, s56
	v_writelane_b32 v252, s36, 45
	s_nop 1
	v_writelane_b32 v252, s37, 46
	v_writelane_b32 v252, s56, 47
	s_addc_u32 s9, s37, s57
	s_mov_b32 s36, s40
	v_writelane_b32 v252, s57, 48
	v_writelane_b32 v252, s8, 49
	s_mov_b64 s[56:57], 0x10080
	s_nop 0
	v_writelane_b32 v252, s9, 50
	s_lshl_b64 s[8:9], s[42:43], 19
	s_add_u32 s20, s28, s8
	v_writelane_b32 v252, s28, 51
	s_addc_u32 s21, s29, s9
	s_lshl_b64 s[10:11], s[10:11], 19
	v_writelane_b32 v252, s29, 52
	v_writelane_b32 v252, s20, 53
	s_nop 1
	v_writelane_b32 v252, s21, 54
	s_add_u32 s20, s30, s10
	v_writelane_b32 v252, s30, 55
	s_addc_u32 s21, s31, s11
	s_add_i32 s2, s3, s2
	s_ashr_i32 s3, s2, 31
	s_lshr_b32 s3, s3, 28
	s_add_i32 s3, s2, s3
	s_and_b32 s13, s3, 0xfff0
	s_sub_i32 s2, s2, s13
	s_bfe_i32 s13, s2, 0x80000
	s_bfe_u32 s13, s13, 0x3000c
	s_add_i32 s13, s2, s13
	s_and_b32 s15, s13, 0xf8
	v_writelane_b32 v252, s31, 56
	s_sub_i32 s2, s2, s15
	s_ashr_i32 s3, s3, 4
	v_writelane_b32 v252, s20, 57
	s_lshl_b32 s3, s3, 3
	s_bfe_i32 s13, s13, 0x80000
	s_sext_i32_i8 s2, s2
	v_writelane_b32 v252, s21, 58
	s_and_b32 s13, 0xffff, s13
	s_add_i32 s20, s3, s2
	s_lshr_b32 s13, s13, 3
	s_mov_b32 s2, s20
	s_add_i32 s13, s13, 6
	s_ashr_i32 s21, s20, 31
	v_writelane_b32 v252, s2, 59
	s_and_b32 s13, s13, 0xff
	s_nop 0
	v_writelane_b32 v252, s3, 60
	s_lshl_b64 s[2:3], s[20:21], 19
	s_add_u32 s2, s18, s2
	s_addc_u32 s3, s19, s3
	v_writelane_b32 v252, s2, 61
	s_nop 1
	v_writelane_b32 v252, s3, 62
	s_lshl_b32 s2, s13, 19
	s_add_u32 s2, s38, s2
	v_writelane_b32 v253, s38, 0
	s_addc_u32 s3, s39, 0
	v_writelane_b32 v252, s13, 63
	v_writelane_b32 v253, s39, 1
	v_writelane_b32 v253, s2, 2
	s_mov_b64 s[38:39], 0x10000
	s_nop 0
	v_writelane_b32 v253, s3, 3
	s_add_u32 s2, s18, s8
	v_writelane_b32 v253, s18, 4
	s_addc_u32 s3, s19, s9
	s_nop 0
	v_writelane_b32 v253, s19, 5
	v_writelane_b32 v253, s2, 6
	s_nop 1
	v_writelane_b32 v253, s3, 7
	s_add_u32 s2, s54, s10
	v_writelane_b32 v253, s2, 8
	s_addc_u32 s2, s55, s11
	v_writelane_b32 v253, s2, 9
	s_mul_i32 s2, s42, 0x160000
	s_add_u32 s2, s22, s2
	v_writelane_b32 v253, s2, 10
	s_mov_b32 s2, s42
	v_writelane_b32 v253, s2, 11
	s_nop 1
	v_writelane_b32 v253, s3, 12
	s_mul_hi_i32 s2, s42, 0x160000
	v_writelane_b32 v253, s22, 13
	s_addc_u32 s2, s23, s2
	s_nop 0
	v_writelane_b32 v253, s23, 14
	v_writelane_b32 v253, s2, 15
	s_mul_i32 s2, s17, 0x160000
	s_add_u32 s3, s54, s2
	s_mul_hi_i32 s2, s17, 0x160000
	s_addc_u32 s8, s55, s2
	s_mul_i32 s2, s17, 0xfff20000
	v_writelane_b32 v253, s3, 16
	s_add_u32 s2, s3, s2
	v_writelane_b32 v253, s2, 17
	v_writelane_b32 v253, s17, 18
	s_mul_hi_i32 s2, s17, 0xfff20000
	v_writelane_b32 v253, s8, 19
	s_addc_u32 s2, s8, s2
	v_writelane_b32 v253, s2, 20
	s_abs_i32 s2, s12
	v_cvt_f32_u32_e32 v1, s2
	s_sub_i32 s3, 0, s2
	v_rcp_iflag_f32_e32 v1, v1
	s_nop 0
	v_mul_f32_e32 v1, 0x4f7ffffe, v1
	v_cvt_u32_f32_e32 v1, v1
	s_nop 0
	v_readfirstlane_b32 s8, v1
	s_mul_i32 s3, s3, s8
	s_mul_hi_u32 s3, s8, s3
	s_add_i32 s8, s8, s3
	s_abs_i32 s3, s7
	s_mul_hi_u32 s8, s3, s8
	s_mul_i32 s8, s8, s2
	s_sub_i32 s3, s3, s8
	s_ashr_i32 s7, s7, 31
	s_sub_i32 s8, s3, s2
	s_cmp_ge_u32 s3, s2
	s_cselect_b32 s3, s8, s3
	s_sub_i32 s8, s3, s2
	s_cmp_ge_u32 s3, s2
	s_cselect_b32 s2, s8, s3
	s_xor_b32 s2, s2, s7
	s_sub_i32 s2, s2, s7
	s_add_i32 s14, s14, s2
	s_and_b32 s2, s2, 7
	s_lshl_b32 s44, s14, 1
	s_cmp_eq_u32 s2, 0
	s_cselect_b64 s[20:21], -1, 0
	s_cmp_eq_u32 s2, 7
	s_cselect_b64 s[2:3], -1, 0
	s_abs_i32 s7, s5
	v_cvt_f32_u32_e32 v1, s7
	s_sub_i32 s8, 0, s7
	s_lshl_b32 s50, s14, 8
	s_ashr_i32 s10, s5, 31
	v_rcp_iflag_f32_e32 v1, v1
	s_nop 0
	v_mul_f32_e32 v1, 0x4f7ffffe, v1
	v_cvt_u32_f32_e32 v1, v1
	s_nop 0
	v_readfirstlane_b32 s9, v1
	s_mul_i32 s8, s8, s9
	s_mul_hi_u32 s8, s9, s8
	s_add_i32 s9, s9, s8
	s_mul_hi_u32 s8, s6, s9
	s_mul_i32 s9, s8, s7
	s_sub_i32 s9, s6, s9
	s_add_i32 s11, s8, 1
	s_sub_i32 s12, s9, s7
	s_cmp_ge_u32 s9, s7
	s_cselect_b32 s8, s11, s8
	s_cselect_b32 s9, s12, s9
	s_sub_i32 s11, s9, s7
	s_add_i32 s12, s8, 1
	s_cmp_ge_u32 s9, s7
	s_cselect_b32 s8, s12, s8
	s_cselect_b32 s7, s11, s9
	s_xor_b32 s8, s8, s10
	s_sub_i32 s10, s8, s10
	s_add_i32 s8, s7, s4
	s_mov_b32 s9, s97
	s_lshl_b32 s7, s10, 1
	s_add_i32 s14, s7, -4
	s_mov_b32 s12, s8
	s_lshl_b64 s[8:9], s[8:9], 17
	v_writelane_b32 v253, s12, 21
	s_add_u32 s8, s24, s8
	s_addc_u32 s9, s25, s9
	v_writelane_b32 v253, s13, 22
	v_writelane_b32 v253, s8, 23
	s_ashr_i32 s15, s14, 31
	s_mul_i32 s10, s10, s5
	v_writelane_b32 v253, s9, 24
	s_mov_b32 s8, s14
	v_writelane_b32 v253, s8, 25
	s_nop 1
	v_writelane_b32 v253, s9, 26
	s_lshl_b64 s[8:9], s[14:15], 17
	s_add_u32 s8, s26, s8
	v_writelane_b32 v253, s26, 27
	s_addc_u32 s9, s27, s9
	s_sub_i32 s5, s6, s10
	v_writelane_b32 v253, s27, 28
	v_writelane_b32 v253, s8, 29
	s_add_i32 s4, s5, s4
	s_add_i32 s5, s7, -3
	v_writelane_b32 v253, s9, 30
	v_writelane_b32 v253, s5, 31
	s_mov_b32 s6, s4
	s_mov_b32 s5, s97
	v_writelane_b32 v253, s6, 32
	s_lshl_b64 s[4:5], s[4:5], 17
	s_add_u32 s4, s24, s4
	v_writelane_b32 v253, s7, 33
	v_writelane_b32 v253, s24, 34
	s_addc_u32 s5, s25, s5
	s_ashr_i32 s65, s64, 31
	v_writelane_b32 v253, s25, 35
	v_writelane_b32 v253, s4, 36
	s_add_i32 s0, s16, s64
	s_ashr_i32 s37, s40, 31
	v_writelane_b32 v253, s5, 37
	v_writelane_b32 v253, s58, 38
	s_lshl_b32 s45, s47, 4
	s_lshl_b64 s[80:81], s[36:37], 10
	v_writelane_b32 v253, s59, 39
	v_writelane_b32 v253, s16, 40
	s_load_dwordx16 s[4:19], s[66:67], 0x0
	v_writelane_b32 v253, s0, 41
	s_lshl_b64 s[0:1], s[64:65], 10
	v_writelane_b32 v253, s0, 42
	s_lshl_b64 s[74:75], s[36:37], 11
	s_lshl_b64 s[68:69], s[36:37], 12
	v_writelane_b32 v253, s1, 43
	s_lshl_b64 s[0:1], s[64:65], 11
	v_writelane_b32 v253, s0, 44
	v_cndmask_b32_e64 v219, 0, 1, s[58:59]
	s_mov_b64 s[40:41], 0x80
	v_writelane_b32 v253, s1, 45
	s_waitcnt lgkmcnt(0)
	s_add_u32 s0, s4, 0x800
	v_writelane_b32 v253, s0, 46
	s_addc_u32 s0, s5, 0
	v_writelane_b32 v253, s0, 47
	s_lshl_b64 s[0:1], s[64:65], 12
	v_writelane_b32 v253, s0, 48
	s_mov_b64 s[58:59], 0x20080
	s_nop 0
	v_writelane_b32 v253, s1, 49
	s_lshl_b64 s[0:1], s[78:79], 6
	s_add_u32 s0, s54, s0
	s_addc_u32 s1, s55, s1
	s_add_u32 s0, s0, 0x4400000
	s_addc_u32 s1, s1, 0
	v_writelane_b32 v253, s0, 50
	s_lshl_b64 s[82:83], s[78:79], 4
	s_nop 0
	v_writelane_b32 v253, s1, 51
	s_lshl_b64 s[0:1], s[78:79], 7
	s_add_u32 s0, s6, s0
	v_writelane_b32 v253, s4, 52
	s_addc_u32 s1, s7, s1
	s_add_u32 s0, s0, 16
	v_writelane_b32 v254, s16, 0
	v_writelane_b32 v254, s17, 1
	v_writelane_b32 v254, s18, 2
	v_writelane_b32 v254, s19, 3
	v_writelane_b32 v254, s0, 4
	s_addc_u32 s0, s1, 0
	v_writelane_b32 v254, s0, 5
	s_lshl_b32 s0, s60, 8
	s_add_i32 s0, s0, 0
	v_writelane_b32 v254, s60, 6
	s_cmp_ge_u32 s60, 4
	s_cbranch_scc1 .Lprio_done
	s_setprio 1
; #define LAS __attribute__((address_space(3)))
; __global__ void __launch_bounds__(NTHREADS, 2) mk_fwd(Args args) {
;     extern __shared__ __attribute__((aligned(16))) unsigned char lds_raw[];
;     LAS unsigned char* lds = (LAS unsigned char*)lds_raw;
;     volatile LAS unsigned* MISC = (volatile LAS unsigned*)(lds + MISC_OFF);
;     const int tid0 = threadIdx.x, lane0 = tid0 & 63, wave0 = __builtin_amdgcn_readfirstlane(tid0 >> 6);
;     const int G = gridDim.x, bx = blockIdx.x;
;     const int vcu = (G % 8 == 0) ? (bx % 8) * (G / 8) + bx / 8 : bx;
;     const int NGW = G * NWAVES;
;     const int NGT = G * NTHREADS;
;     unsigned char* ws = args.ws; float* out = args.out;
;     for (int u = tid0; u < (LDS_BYTES - LDSCTL_OFF) / 4; u += NTHREADS) ((LAS unsigned*)(lds + LDSCTL_OFF))[u] = 0u;
;     __syncthreads();
;     XcdBarrier bar = xcd_barrier_post((unsigned*)(ws + WS_CTL) + CW_BAR, MISC + 8, wave0);
.Lprio_done:
	s_add_i32 s0, s0, 0x24800
	v_writelane_b32 v254, s0, 7
	s_lshl_b32 s0, s46, 6
	v_writelane_b32 v254, s0, 8
	s_lshl_b32 s0, s47, 6
	s_lshl_b64 s[84:85], s[78:79], 5
	v_writelane_b32 v254, s0, 9
	s_add_u32 s0, s54, 0x4400
	s_addc_u32 s1, s55, 0
	v_writelane_b32 v254, s0, 10
	s_add_u32 s95, s54, 0x9100
	s_addc_u32 s86, s55, 0
	v_writelane_b32 v254, s1, 11
	s_xor_b64 s[0:1], s[2:3], -1
	v_writelane_b32 v254, s0, 12
	v_writelane_b32 v253, s5, 53
	v_writelane_b32 v253, s6, 54
	v_writelane_b32 v254, s1, 13
	v_readfirstlane_b32 s0, v0
	v_writelane_b32 v253, s7, 55
	s_load_dwordx4 s[4:7], s[66:67], 0x90
	v_writelane_b32 v254, s0, 14
	s_add_i32 s0, 0, 0x24964
	v_writelane_b32 v254, s0, 15
	s_add_i32 s0, 0, 0x24968
	v_writelane_b32 v254, s0, 16
	s_add_i32 s0, 0, 0x24970
	v_writelane_b32 v254, s0, 17
	s_add_i32 s0, 0, 0x24000
	v_writelane_b32 v254, s0, 18
	s_add_i32 s0, 0, 0x24960
	v_writelane_b32 v254, s0, 19
	v_writelane_b32 v253, s8, 56
	s_waitcnt lgkmcnt(0)
	v_writelane_b32 v254, s4, 20
	v_writelane_b32 v253, s9, 57
	v_writelane_b32 v253, s10, 58
	v_writelane_b32 v254, s5, 21
	v_writelane_b32 v254, s6, 22
	v_writelane_b32 v253, s11, 59
	v_writelane_b32 v254, s7, 23
	s_load_dwordx8 s[4:11], s[66:67], 0x70
	s_mov_b32 s2, s36
	v_writelane_b32 v253, s12, 60
	v_writelane_b32 v253, s13, 61
	v_writelane_b32 v253, s14, 62
	s_waitcnt lgkmcnt(0)
	v_writelane_b32 v254, s4, 24
	v_writelane_b32 v253, s15, 63
	s_movk_i32 s46, 0x3000
	v_writelane_b32 v254, s5, 25
	v_writelane_b32 v254, s6, 26
	v_writelane_b32 v254, s7, 27
	v_writelane_b32 v254, s8, 28
	v_writelane_b32 v254, s9, 29
	v_writelane_b32 v254, s10, 30
	v_writelane_b32 v254, s11, 31
	s_load_dwordx8 s[4:11], s[66:67], 0x40
	s_mov_b64 s[60:61], 0x20000
	s_mov_b64 s[0:1], 0x30000
	s_waitcnt lgkmcnt(0)
	v_writelane_b32 v254, s4, 32
	s_nop 1
	v_writelane_b32 v254, s5, 33
	v_writelane_b32 v254, s6, 34
	v_writelane_b32 v254, s7, 35
	v_writelane_b32 v254, s8, 36
	v_writelane_b32 v254, s9, 37
	v_writelane_b32 v254, s10, 38
	v_writelane_b32 v254, s11, 39
	v_writelane_b32 v254, s2, 40
	s_nop 1
	v_writelane_b32 v254, s3, 41
	v_writelane_b32 v254, s44, 42
	v_writelane_b32 v254, s20, 43
	s_nop 1
	v_writelane_b32 v254, s21, 44
	v_writelane_b32 v254, s50, 45
	v_writelane_b32 v254, s80, 46
	s_nop 1
	v_writelane_b32 v254, s81, 47
	v_writelane_b32 v254, s74, 48
	s_nop 1
	v_writelane_b32 v254, s75, 49
	v_writelane_b32 v254, s68, 50
	s_nop 1
	v_writelane_b32 v254, s69, 51
	v_writelane_b32 v254, s94, 52
	v_writelane_b32 v254, s82, 53
	s_nop 1
	v_writelane_b32 v254, s83, 54
	v_writelane_b32 v254, s84, 55
	s_nop 1
	v_writelane_b32 v254, s85, 56
	v_writelane_b32 v254, s95, 57
	v_writelane_b32 v254, s86, 58
	v_writelane_b32 v254, s87, 59
	v_writelane_b32 v254, s66, 60
	s_nop 1
	v_writelane_b32 v254, s67, 61
	v_writelane_b32 v254, s92, 62
	v_writelane_b32 v254, s52, 63
	s_nop 1
	v_writelane_b32 v255, s53, 0
	v_writelane_b32 v255, s54, 1
	v_writelane_b32 v255, s55, 2
	s_branch .LBB0_17

; #define PG8_STAGE(bufoff, gbase, voff, h64) do { \
;         __builtin_amdgcn_global_load_lds((const unsigned*)((const char*)(gbase) + (voff)), (LAS unsigned*)(lds + (bufoff) + ldsw), 16, 0, 0); \
;         __builtin_amdgcn_global_load_lds((const unsigned*)((const char*)(gbase) + (h64) + (voff)), (LAS unsigned*)(lds + (bufoff) + ldsw + 8192), 16, 0, 0); } while (0)
; #define PG8_LDA(dst, b, h) do { _Pragma("unroll") for (int m = 0; m < 4; ++m) { dst[m].lo = *(const LAS f16x8*)(lds + PG8_SA(b, h) + aoff + m * 2048); dst[m].hi = *(const LAS f16x8*)(lds + PG8_SA(b, h) + aoff + m * 2048 + 1024); } } while (0)
; #define PG8_LDB(dst, b, h) do { _Pragma("unroll") for (int n = 0; n < 2; ++n) { dst[n].lo = *(const LAS f16x8*)(lds + PG8_SB(b, h) + boff + n * 2048); dst[n].hi = *(const LAS f16x8*)(lds + PG8_SB(b, h) + boff + n * 2048 + 1024); } } while (0)
; #define PG8_WAIT_V(n) asm volatile("s_waitcnt vmcnt(" #n ")" ::: "memory")
; #define PG8_WAIT_L(n) asm volatile("s_waitcnt lgkmcnt(" #n ")" ::: "memory")
; #define PG8_BAR __builtin_amdgcn_s_barrier()
; #define PG8_SCHED __builtin_amdgcn_sched_barrier(0)
; template <bool F8 = false, class Sched, class Epi>
; __device__ __forceinline__ void gemm_phase(LAS unsigned char* lds, const Sched& S, const Epi& E) {
;     ...
;             PG8_LDB(B0, 0, 0); PG8_LDB(B1, 0, 1); PG8_SCHED; PG8_LDA(At, 0, 0); PG8_STAGE(PG8_SA(1, 1), a1 + chs, cvA, ch64);
;             PG8_WAIT_V(8); PG8_WAIT_L(0); PG8_BAR; PG8_MMA(0, 0, At, B0); PG8_MMA(0, 1, At, B1); PG8_BAR; PG8_SCHED;
;             PG8_LDA(At, 0, 1); PG8_STAGE(PG8_SB(0, 0), b2, vB2, h2); PG8_STAGE(PG8_SB(0, 1), b2 + bhs2, vB2, h2); PG8_STAGE(PG8_SA(0, 0), a2, vA2, h2);
;             PG8_WAIT_V(8); PG8_WAIT_L(0); PG8_BAR; PG8_MMA(1, 0, At, B0); PG8_MMA(1, 1, At, B1); PG8_BAR; PG8_SCHED;
;             PG8_LDB(B0, 1, 0); PG8_LDB(B1, 1, 1); PG8_SCHED; PG8_LDA(At, 1, 0); PG8_STAGE(PG8_SA(0, 1), a2 + hs2, vA2, h2);
;             PG8_WAIT_V(8); PG8_WAIT_L(0); PG8_BAR; PG8_MMA(0, 0, At, B0); PG8_MMA(0, 1, At, B1); PG8_BAR; PG8_SCHED;
.LBB0_73:
	s_add_u32 s24, s12, s8
	s_addc_u32 s25, s13, s9
	s_add_u32 s26, s24, 0x100
	s_addc_u32 s27, s25, 0
	s_add_u32 s36, s71, s8
	s_addc_u32 s68, s72, s9
	s_cmpk_eq_i32 s8, 0x300
	s_cselect_b64 vcc, -1, 0
	s_and_b64 s[24:25], vcc, exec
	s_cselect_b32 s25, s73, s27
	s_cselect_b32 s24, s74, s26
	s_cselect_b32 s27, s75, s68
	s_cselect_b32 s26, s80, s36
	s_add_i32 s36, 0, 0x10000
	s_add_i32 s68, 0, 0x14000
	v_add_u32_e32 v0, s36, v163
	v_add_u32_e32 v12, s68, v163
	ds_read_b128 v[16:19], v0
	ds_read_b128 v[20:23], v0 offset:1024
	ds_read_b128 v[24:27], v0 offset:2048
	ds_read_b128 v[28:31], v0 offset:3072
	ds_read_b128 v[0:3], v12
	ds_read_b128 v[4:7], v12 offset:1024
	ds_read_b128 v[8:11], v12 offset:2048
	ds_read_b128 v[12:15], v12 offset:3072
	v_cndmask_b32_e32 v32, v164, v166, vcc
	v_cndmask_b32_e32 v172, v162, v175, vcc
	v_lshl_add_u64 v[170:171], v[168:169], 0, s[8:9]
	v_lshl_add_u64 v[192:193], v[170:171], 0, s[58:59]
	s_add_i32 m0, s31, 0xc000
	ds_read_b128 v[176:179], v174
	ds_read_b128 v[180:183], v174 offset:1024
	ds_read_b128 v[184:187], v174 offset:2048
	ds_read_b128 v[188:191], v174 offset:3072
	ds_read_b128 v[198:201], v174 offset:4096
	ds_read_b128 v[202:205], v174 offset:5120
	ds_read_b128 v[206:209], v174 offset:6144
	ds_read_b128 v[210:213], v174 offset:7168
	global_load_lds_dwordx4 v[192:193], off
	v_lshl_add_u64 v[170:171], v[170:171], 0, s[76:77]
	s_add_i32 m0, s31, 0xe000
	s_nop 0
	global_load_lds_dwordx4 v[170:171], off
	s_waitcnt vmcnt(8)
	s_waitcnt lgkmcnt(0)
	s_barrier
	v_mfma_scale_f32_16x16x128_f8f6f4 v[158:161], v[16:23], v[176:183], v[158:161], v220, v221 op_sel_hi:[0,0,0]
	v_mfma_scale_f32_16x16x128_f8f6f4 v[154:157], v[24:31], v[176:183], v[154:157], v220, v221 op_sel_hi:[0,0,0]
	v_mfma_scale_f32_16x16x128_f8f6f4 v[150:153], v[16:23], v[184:191], v[150:153], v220, v221 op_sel_hi:[0,0,0]
	v_mfma_scale_f32_16x16x128_f8f6f4 v[146:149], v[24:31], v[184:191], v[146:149], v220, v221 op_sel_hi:[0,0,0]
	v_mfma_scale_f32_16x16x128_f8f6f4 v[142:145], v[16:23], v[198:205], v[142:145], v220, v221 op_sel_hi:[0,0,0]
	v_mfma_scale_f32_16x16x128_f8f6f4 v[138:141], v[24:31], v[198:205], v[138:141], v220, v221 op_sel_hi:[0,0,0]
	v_mfma_scale_f32_16x16x128_f8f6f4 v[134:137], v[16:23], v[206:213], v[134:137], v220, v221 op_sel_hi:[0,0,0]
	v_mfma_scale_f32_16x16x128_f8f6f4 v[130:133], v[24:31], v[206:213], v[130:133], v220, v221 op_sel_hi:[0,0,0]
	v_mfma_scale_f32_16x16x128_f8f6f4 v[126:129], v[0:7], v[176:183], v[126:129], v220, v221 op_sel_hi:[0,0,0]
	v_mfma_scale_f32_16x16x128_f8f6f4 v[122:125], v[8:15], v[176:183], v[122:125], v220, v221 op_sel_hi:[0,0,0]
	v_mfma_scale_f32_16x16x128_f8f6f4 v[118:121], v[0:7], v[184:191], v[118:121], v220, v221 op_sel_hi:[0,0,0]
	v_mfma_scale_f32_16x16x128_f8f6f4 v[114:117], v[8:15], v[184:191], v[114:117], v220, v221 op_sel_hi:[0,0,0]
	v_mfma_scale_f32_16x16x128_f8f6f4 v[110:113], v[0:7], v[198:205], v[110:113], v220, v221 op_sel_hi:[0,0,0]
	v_mfma_scale_f32_16x16x128_f8f6f4 v[106:109], v[8:15], v[198:205], v[106:109], v220, v221 op_sel_hi:[0,0,0]
	v_mfma_scale_f32_16x16x128_f8f6f4 v[102:105], v[0:7], v[206:213], v[102:105], v220, v221 op_sel_hi:[0,0,0]
	v_mfma_scale_f32_16x16x128_f8f6f4 v[98:101], v[8:15], v[206:213], v[98:101], v220, v221 op_sel_hi:[0,0,0]
	s_barrier
	v_mov_b32_e32 v173, v33
	s_add_i32 s36, s36, s49
	v_lshl_add_u64 v[170:171], s[26:27], 0, v[172:173]
	s_mov_b32 m0, s36
	ds_read_b128 v[176:179], v174 offset:16384
	ds_read_b128 v[180:183], v174 offset:17408
	ds_read_b128 v[184:187], v174 offset:18432
	ds_read_b128 v[188:191], v174 offset:19456
	ds_read_b128 v[198:201], v174 offset:20480
	ds_read_b128 v[202:205], v174 offset:21504
	ds_read_b128 v[206:209], v174 offset:22528
	ds_read_b128 v[210:213], v174 offset:23552
	global_load_lds_dwordx4 v172, s[26:27]
	v_lshl_add_u64 v[172:173], v[170:171], 0, s[38:39]
	s_add_i32 m0, s36, 0x2000
	s_add_i32 s26, s68, s49
	global_load_lds_dwordx4 v[172:173], off
	v_lshl_add_u64 v[172:173], v[170:171], 0, s[60:61]
	s_mov_b32 m0, s26
	s_nop 0
	global_load_lds_dwordx4 v[172:173], off
	v_lshl_add_u64 v[172:173], v[170:171], 0, s[0:1]
	s_add_i32 m0, s26, 0x2000
	s_nop 0
	global_load_lds_dwordx4 v[172:173], off
	v_lshl_add_u64 v[172:173], s[24:25], 0, v[32:33]
	s_mov_b32 m0, s31
	v_lshl_add_u64 v[192:193], v[172:173], 0, s[38:39]
	global_load_lds_dwordx4 v[172:173], off
	s_mov_b32 m0, s34
	s_nop 0
	global_load_lds_dwordx4 v[192:193], off
	s_waitcnt vmcnt(8)
	s_waitcnt lgkmcnt(0)
	s_barrier
	v_mfma_scale_f32_16x16x128_f8f6f4 v[94:97], v[16:23], v[176:183], v[94:97], v220, v221 op_sel_hi:[0,0,0]
	v_mfma_scale_f32_16x16x128_f8f6f4 v[90:93], v[24:31], v[176:183], v[90:93], v220, v221 op_sel_hi:[0,0,0]
	v_mfma_scale_f32_16x16x128_f8f6f4 v[86:89], v[16:23], v[184:191], v[86:89], v220, v221 op_sel_hi:[0,0,0]
	v_mfma_scale_f32_16x16x128_f8f6f4 v[82:85], v[24:31], v[184:191], v[82:85], v220, v221 op_sel_hi:[0,0,0]
	v_mfma_scale_f32_16x16x128_f8f6f4 v[78:81], v[16:23], v[198:205], v[78:81], v220, v221 op_sel_hi:[0,0,0]
	v_mfma_scale_f32_16x16x128_f8f6f4 v[74:77], v[24:31], v[198:205], v[74:77], v220, v221 op_sel_hi:[0,0,0]
	v_mfma_scale_f32_16x16x128_f8f6f4 v[70:73], v[16:23], v[206:213], v[70:73], v220, v221 op_sel_hi:[0,0,0]
	v_mfma_scale_f32_16x16x128_f8f6f4 v[66:69], v[24:31], v[206:213], v[66:69], v220, v221 op_sel_hi:[0,0,0]
	v_mfma_scale_f32_16x16x128_f8f6f4 v[62:65], v[0:7], v[176:183], v[62:65], v220, v221 op_sel_hi:[0,0,0]
	v_mfma_scale_f32_16x16x128_f8f6f4 v[58:61], v[8:15], v[176:183], v[58:61], v220, v221 op_sel_hi:[0,0,0]
	v_mfma_scale_f32_16x16x128_f8f6f4 v[54:57], v[0:7], v[184:191], v[54:57], v220, v221 op_sel_hi:[0,0,0]
	v_mfma_scale_f32_16x16x128_f8f6f4 v[50:53], v[8:15], v[184:191], v[50:53], v220, v221 op_sel_hi:[0,0,0]
	v_mfma_scale_f32_16x16x128_f8f6f4 v[46:49], v[0:7], v[198:205], v[46:49], v220, v221 op_sel_hi:[0,0,0]
	v_mfma_scale_f32_16x16x128_f8f6f4 v[42:45], v[8:15], v[198:205], v[42:45], v220, v221 op_sel_hi:[0,0,0]
	v_mfma_scale_f32_16x16x128_f8f6f4 v[38:41], v[0:7], v[206:213], v[38:41], v220, v221 op_sel_hi:[0,0,0]
	v_mfma_scale_f32_16x16x128_f8f6f4 v[34:37], v[8:15], v[206:213], v[34:37], v220, v221 op_sel_hi:[0,0,0]
	s_barrier
; #define PG8_STAGE(bufoff, gbase, voff, h64) do { \
;         __builtin_amdgcn_global_load_lds((const unsigned*)((const char*)(gbase) + (voff)), (LAS unsigned*)(lds + (bufoff) + ldsw), 16, 0, 0); \
;         __builtin_amdgcn_global_load_lds((const unsigned*)((const char*)(gbase) + (h64) + (voff)), (LAS unsigned*)(lds + (bufoff) + ldsw + 8192), 16, 0, 0); } while (0)
; #define PG8_LDA(dst, b, h) do { _Pragma("unroll") for (int m = 0; m < 4; ++m) { dst[m].lo = *(const LAS f16x8*)(lds + PG8_SA(b, h) + aoff + m * 2048); dst[m].hi = *(const LAS f16x8*)(lds + PG8_SA(b, h) + aoff + m * 2048 + 1024); } } while (0)
; #define PG8_LDB(dst, b, h) do { _Pragma("unroll") for (int n = 0; n < 2; ++n) { dst[n].lo = *(const LAS f16x8*)(lds + PG8_SB(b, h) + boff + n * 2048); dst[n].hi = *(const LAS f16x8*)(lds + PG8_SB(b, h) + boff + n * 2048 + 1024); } } while (0)
; #define PG8_WAIT_V(n) asm volatile("s_waitcnt vmcnt(" #n ")" ::: "memory")
; #define PG8_WAIT_L(n) asm volatile("s_waitcnt lgkmcnt(" #n ")" ::: "memory")
; #define PG8_BAR __builtin_amdgcn_s_barrier()
; #define PG8_SCHED __builtin_amdgcn_sched_barrier(0)
; template <bool F8 = false, class Sched, class Epi>
; __device__ __forceinline__ void gemm_phase(LAS unsigned char* lds, const Sched& S, const Epi& E) {
;     ...
;             PG8_LDA(At, 0, 1); PG8_STAGE(PG8_SB(0, 0), b2, vB2, h2); PG8_STAGE(PG8_SB(0, 1), b2 + bhs2, vB2, h2); PG8_STAGE(PG8_SA(0, 0), a2, vA2, h2);
;             PG8_WAIT_V(8); PG8_WAIT_L(0); PG8_BAR; PG8_MMA(1, 0, At, B0); PG8_MMA(1, 1, At, B1); PG8_BAR; PG8_SCHED;
;             PG8_LDB(B0, 1, 0); PG8_LDB(B1, 1, 1); PG8_SCHED; PG8_LDA(At, 1, 0); PG8_STAGE(PG8_SA(0, 1), a2 + hs2, vA2, h2);
;             PG8_WAIT_V(8); PG8_WAIT_L(0); PG8_BAR; PG8_MMA(0, 0, At, B0); PG8_MMA(0, 1, At, B1); PG8_BAR; PG8_SCHED;
;             PG8_LDA(At, 1, 1); PG8_STAGE(PG8_SB(1, 0), b3, vB2, h2); PG8_STAGE(PG8_SB(1, 1), b3 + bhs2, vB2, h2); PG8_STAGE(PG8_SA(1, 0), a3, vA2, h2);
;             PG8_WAIT_V(8); PG8_WAIT_L(0); PG8_BAR; PG8_MMA(1, 0, At, B0); PG8_MMA(1, 1, At, B1); PG8_BAR; PG8_SCHED;
;         }
;         if (wr == 0) PG8_BAR;
	s_add_i32 s24, 0, 0x18000
	s_add_i32 s25, 0, 0x1c000
	v_add_u32_e32 v12, s24, v163
	v_add_u32_e32 v28, s25, v163
	ds_read_b128 v[0:3], v12
	ds_read_b128 v[4:7], v12 offset:1024
	ds_read_b128 v[8:11], v12 offset:2048
	ds_read_b128 v[12:15], v12 offset:3072
	ds_read_b128 v[16:19], v28
	ds_read_b128 v[20:23], v28 offset:1024
	ds_read_b128 v[24:27], v28 offset:2048
	ds_read_b128 v[28:31], v28 offset:3072
	s_mov_b32 m0, s35
	v_lshl_add_u64 v[192:193], v[172:173], 0, s[60:61]
	ds_read_b128 v[176:179], v174 offset:32768
	ds_read_b128 v[180:183], v174 offset:33792
	ds_read_b128 v[184:187], v174 offset:34816
	ds_read_b128 v[188:191], v174 offset:35840
	ds_read_b128 v[198:201], v174 offset:36864
	ds_read_b128 v[202:205], v174 offset:37888
	ds_read_b128 v[206:209], v174 offset:38912
	ds_read_b128 v[210:213], v174 offset:39936
	global_load_lds_dwordx4 v[192:193], off
	v_lshl_add_u64 v[192:193], v[172:173], 0, s[0:1]
	s_mov_b32 m0, s37
	s_nop 0
	global_load_lds_dwordx4 v[192:193], off
	s_waitcnt vmcnt(8)
	s_waitcnt lgkmcnt(0)
	s_barrier
	v_mfma_scale_f32_16x16x128_f8f6f4 v[158:161], v[0:7], v[176:183], v[158:161], v220, v221 op_sel_hi:[0,0,0]
	v_mfma_scale_f32_16x16x128_f8f6f4 v[154:157], v[8:15], v[176:183], v[154:157], v220, v221 op_sel_hi:[0,0,0]
	v_mfma_scale_f32_16x16x128_f8f6f4 v[150:153], v[0:7], v[184:191], v[150:153], v220, v221 op_sel_hi:[0,0,0]
	v_mfma_scale_f32_16x16x128_f8f6f4 v[146:149], v[8:15], v[184:191], v[146:149], v220, v221 op_sel_hi:[0,0,0]
	v_mfma_scale_f32_16x16x128_f8f6f4 v[142:145], v[0:7], v[198:205], v[142:145], v220, v221 op_sel_hi:[0,0,0]
	v_mfma_scale_f32_16x16x128_f8f6f4 v[138:141], v[8:15], v[198:205], v[138:141], v220, v221 op_sel_hi:[0,0,0]
	v_mfma_scale_f32_16x16x128_f8f6f4 v[134:137], v[0:7], v[206:213], v[134:137], v220, v221 op_sel_hi:[0,0,0]
	v_mfma_scale_f32_16x16x128_f8f6f4 v[130:133], v[8:15], v[206:213], v[130:133], v220, v221 op_sel_hi:[0,0,0]
	v_mfma_scale_f32_16x16x128_f8f6f4 v[126:129], v[16:23], v[176:183], v[126:129], v220, v221 op_sel_hi:[0,0,0]
	v_mfma_scale_f32_16x16x128_f8f6f4 v[122:125], v[24:31], v[176:183], v[122:125], v220, v221 op_sel_hi:[0,0,0]
	v_mfma_scale_f32_16x16x128_f8f6f4 v[118:121], v[16:23], v[184:191], v[118:121], v220, v221 op_sel_hi:[0,0,0]
	v_mfma_scale_f32_16x16x128_f8f6f4 v[114:117], v[24:31], v[184:191], v[114:117], v220, v221 op_sel_hi:[0,0,0]
	v_mfma_scale_f32_16x16x128_f8f6f4 v[110:113], v[16:23], v[198:205], v[110:113], v220, v221 op_sel_hi:[0,0,0]
	v_mfma_scale_f32_16x16x128_f8f6f4 v[106:109], v[24:31], v[198:205], v[106:109], v220, v221 op_sel_hi:[0,0,0]
	v_mfma_scale_f32_16x16x128_f8f6f4 v[102:105], v[16:23], v[206:213], v[102:105], v220, v221 op_sel_hi:[0,0,0]
	v_mfma_scale_f32_16x16x128_f8f6f4 v[98:101], v[24:31], v[206:213], v[98:101], v220, v221 op_sel_hi:[0,0,0]
	s_barrier
	s_add_i32 s24, s24, s49
	v_lshl_add_u64 v[192:193], v[170:171], 0, s[40:41]
	s_mov_b32 m0, s24
	ds_read_b128 v[176:179], v174 offset:49152
	ds_read_b128 v[180:183], v174 offset:50176
	ds_read_b128 v[184:187], v174 offset:51200
	ds_read_b128 v[188:191], v174 offset:52224
	ds_read_b128 v[198:201], v174 offset:53248
	ds_read_b128 v[202:205], v174 offset:54272
	ds_read_b128 v[206:209], v174 offset:55296
	ds_read_b128 v[210:213], v174 offset:56320
	global_load_lds_dwordx4 v[192:193], off
	v_lshl_add_u64 v[192:193], v[170:171], 0, s[56:57]
	s_add_i32 m0, s24, 0x2000
	s_add_i32 s24, s25, s49
	global_load_lds_dwordx4 v[192:193], off
	v_lshl_add_u64 v[192:193], v[170:171], 0, s[58:59]
	s_mov_b32 m0, s24
	v_lshl_add_u64 v[170:171], v[170:171], 0, s[76:77]
	global_load_lds_dwordx4 v[192:193], off
	s_add_i32 m0, s24, 0x2000
	s_nop 0
	global_load_lds_dwordx4 v[170:171], off
	v_lshl_add_u64 v[170:171], v[172:173], 0, s[40:41]
	s_mov_b32 m0, s42
	s_nop 0
	global_load_lds_dwordx4 v[170:171], off
	v_lshl_add_u64 v[170:171], v[172:173], 0, s[56:57]
	s_mov_b32 m0, s43
	s_nop 0
	global_load_lds_dwordx4 v[170:171], off
	s_waitcnt vmcnt(8)
	s_waitcnt lgkmcnt(0)
	s_barrier
	v_mfma_scale_f32_16x16x128_f8f6f4 v[94:97], v[0:7], v[176:183], v[94:97], v220, v221 op_sel_hi:[0,0,0]
	v_mfma_scale_f32_16x16x128_f8f6f4 v[90:93], v[8:15], v[176:183], v[90:93], v220, v221 op_sel_hi:[0,0,0]
	v_mfma_scale_f32_16x16x128_f8f6f4 v[86:89], v[0:7], v[184:191], v[86:89], v220, v221 op_sel_hi:[0,0,0]
	v_mfma_scale_f32_16x16x128_f8f6f4 v[82:85], v[8:15], v[184:191], v[82:85], v220, v221 op_sel_hi:[0,0,0]
	v_mfma_scale_f32_16x16x128_f8f6f4 v[78:81], v[0:7], v[198:205], v[78:81], v220, v221 op_sel_hi:[0,0,0]
	v_mfma_scale_f32_16x16x128_f8f6f4 v[74:77], v[8:15], v[198:205], v[74:77], v220, v221 op_sel_hi:[0,0,0]
	v_mfma_scale_f32_16x16x128_f8f6f4 v[70:73], v[0:7], v[206:213], v[70:73], v220, v221 op_sel_hi:[0,0,0]
	v_mfma_scale_f32_16x16x128_f8f6f4 v[66:69], v[8:15], v[206:213], v[66:69], v220, v221 op_sel_hi:[0,0,0]
	v_mfma_scale_f32_16x16x128_f8f6f4 v[62:65], v[16:23], v[176:183], v[62:65], v220, v221 op_sel_hi:[0,0,0]
	v_mfma_scale_f32_16x16x128_f8f6f4 v[58:61], v[24:31], v[176:183], v[58:61], v220, v221 op_sel_hi:[0,0,0]
	v_mfma_scale_f32_16x16x128_f8f6f4 v[54:57], v[16:23], v[184:191], v[54:57], v220, v221 op_sel_hi:[0,0,0]
	v_mfma_scale_f32_16x16x128_f8f6f4 v[50:53], v[24:31], v[184:191], v[50:53], v220, v221 op_sel_hi:[0,0,0]
	v_mfma_scale_f32_16x16x128_f8f6f4 v[46:49], v[16:23], v[198:205], v[46:49], v220, v221 op_sel_hi:[0,0,0]
	v_mfma_scale_f32_16x16x128_f8f6f4 v[42:45], v[24:31], v[198:205], v[42:45], v220, v221 op_sel_hi:[0,0,0]
	v_mfma_scale_f32_16x16x128_f8f6f4 v[38:41], v[16:23], v[206:213], v[38:41], v220, v221 op_sel_hi:[0,0,0]
	v_mfma_scale_f32_16x16x128_f8f6f4 v[34:37], v[24:31], v[206:213], v[34:37], v220, v221 op_sel_hi:[0,0,0]
	s_barrier
	s_add_i32 s81, s81, 2
	s_add_u32 s8, s8, 0x100
	s_addc_u32 s9, s9, 0
	s_cmp_gt_u32 s81, 5
	s_cbranch_scc0 .LBB0_73
	v_readlane_b32 s8, v251, 12
	v_readlane_b32 s9, v251, 13
	s_and_b64 vcc, exec, s[8:9]
	s_cbranch_vccz .LBB0_76
	s_barrier

; #define PG8_STAGE(bufoff, gbase, voff, h64) do { \
;         __builtin_amdgcn_global_load_lds((const unsigned*)((const char*)(gbase) + (voff)), (LAS unsigned*)(lds + (bufoff) + ldsw), 16, 0, 0); \
;         __builtin_amdgcn_global_load_lds((const unsigned*)((const char*)(gbase) + (h64) + (voff)), (LAS unsigned*)(lds + (bufoff) + ldsw + 8192), 16, 0, 0); } while (0)
; #define PG8_LDA(dst, b, h) do { _Pragma("unroll") for (int m = 0; m < 4; ++m) { dst[m].lo = *(const LAS f16x8*)(lds + PG8_SA(b, h) + aoff + m * 2048); dst[m].hi = *(const LAS f16x8*)(lds + PG8_SA(b, h) + aoff + m * 2048 + 1024); } } while (0)
; #define PG8_LDB(dst, b, h) do { _Pragma("unroll") for (int n = 0; n < 2; ++n) { dst[n].lo = *(const LAS f16x8*)(lds + PG8_SB(b, h) + boff + n * 2048); dst[n].hi = *(const LAS f16x8*)(lds + PG8_SB(b, h) + boff + n * 2048 + 1024); } } while (0)
; #define PG8_WAIT_V(n) asm volatile("s_waitcnt vmcnt(" #n ")" ::: "memory")
; #define PG8_WAIT_L(n) asm volatile("s_waitcnt lgkmcnt(" #n ")" ::: "memory")
; #define PG8_BAR __builtin_amdgcn_s_barrier()
; #define PG8_SCHED __builtin_amdgcn_sched_barrier(0)
; template <bool F8 = false, class Sched, class Epi>
; __device__ __forceinline__ void gemm_phase(LAS unsigned char* lds, const Sched& S, const Epi& E) {
;     ...
;             PG8_LDB(B0, 0, 0); PG8_LDB(B1, 0, 1); PG8_SCHED; PG8_LDA(At, 0, 0); PG8_STAGE(PG8_SA(1, 1), a1 + chs, cvA, ch64);
;             PG8_WAIT_V(8); PG8_WAIT_L(0); PG8_BAR; PG8_MMA(0, 0, At, B0); PG8_MMA(0, 1, At, B1); PG8_BAR; PG8_SCHED;
;             PG8_LDA(At, 0, 1); PG8_STAGE(PG8_SB(0, 0), b2, vB2, h2); PG8_STAGE(PG8_SB(0, 1), b2 + bhs2, vB2, h2); PG8_STAGE(PG8_SA(0, 0), a2, vA2, h2);
;             PG8_WAIT_V(8); PG8_WAIT_L(0); PG8_BAR; PG8_MMA(1, 0, At, B0); PG8_MMA(1, 1, At, B1); PG8_BAR; PG8_SCHED;
;             PG8_LDB(B0, 1, 0); PG8_LDB(B1, 1, 1); PG8_SCHED; PG8_LDA(At, 1, 0); PG8_STAGE(PG8_SA(0, 1), a2 + hs2, vA2, h2);
;             PG8_WAIT_V(8); PG8_WAIT_L(0); PG8_BAR; PG8_MMA(0, 0, At, B0); PG8_MMA(0, 1, At, B1); PG8_BAR; PG8_SCHED;
.Lk16_sel:
	s_add_i32 s79, s79, 2
	s_add_u32 vcc_lo, s14, s10
	s_addc_u32 vcc_hi, s15, s11
	s_add_u32 vcc_lo, vcc_lo, 0x100
	s_addc_u32 vcc_hi, vcc_hi, 0
	s_and_b64 s[86:87], exec, s[86:87]
	s_cselect_b32 vcc_hi, s29, vcc_hi
	s_cselect_b32 vcc_lo, s96, vcc_lo
	s_add_i32 s86, 0, 0x10000
	s_add_i32 s45, 0, 0x14000
	s_waitcnt vmcnt(8)
	s_waitcnt lgkmcnt(0)
	s_barrier
	v_mfma_f32_16x16x32_f16 v[128:131], v[138:141], v[170:173], v[128:131]
	v_mfma_f32_16x16x32_f16 v[124:127], v[146:149], v[170:173], v[124:127]
	v_mfma_f32_16x16x32_f16 v[112:115], v[138:141], v[178:181], v[112:115]
	v_mfma_f32_16x16x32_f16 v[108:111], v[146:149], v[178:181], v[108:111]
	v_mfma_f32_16x16x32_f16 v[96:99], v[138:141], v[198:201], v[96:99]
	v_mfma_f32_16x16x32_f16 v[92:95], v[146:149], v[198:201], v[92:95]
	v_mfma_f32_16x16x32_f16 v[80:83], v[138:141], v[208:211], v[80:83]
	v_mfma_f32_16x16x32_f16 v[76:79], v[146:149], v[208:211], v[76:79]
	v_mfma_f32_16x16x32_f16 v[128:131], v[142:145], v[174:177], v[128:131]
	v_mfma_f32_16x16x32_f16 v[124:127], v[150:153], v[174:177], v[124:127]
	v_mfma_f32_16x16x32_f16 v[112:115], v[142:145], v[190:193], v[112:115]
	v_mfma_f32_16x16x32_f16 v[108:111], v[150:153], v[190:193], v[108:111]
	v_mfma_f32_16x16x32_f16 v[96:99], v[142:145], v[204:207], v[96:99]
	v_mfma_f32_16x16x32_f16 v[92:95], v[150:153], v[204:207], v[92:95]
	v_mfma_f32_16x16x32_f16 v[80:83], v[142:145], v[212:215], v[80:83]
	v_mfma_f32_16x16x32_f16 v[76:79], v[150:153], v[212:215], v[76:79]
	v_mfma_f32_16x16x32_f16 v[120:123], v[154:157], v[170:173], v[120:123]
	v_mfma_f32_16x16x32_f16 v[116:119], v[162:165], v[170:173], v[116:119]
	v_mfma_f32_16x16x32_f16 v[104:107], v[154:157], v[178:181], v[104:107]
	v_mfma_f32_16x16x32_f16 v[100:103], v[162:165], v[178:181], v[100:103]
	v_mfma_f32_16x16x32_f16 v[88:91], v[154:157], v[198:201], v[88:91]
	v_mfma_f32_16x16x32_f16 v[84:87], v[162:165], v[198:201], v[84:87]
	v_mfma_f32_16x16x32_f16 v[72:75], v[154:157], v[208:211], v[72:75]
	v_mfma_f32_16x16x32_f16 v[68:71], v[162:165], v[208:211], v[68:71]
	v_mfma_f32_16x16x32_f16 v[120:123], v[158:161], v[174:177], v[120:123]
	v_mfma_f32_16x16x32_f16 v[116:119], v[166:169], v[174:177], v[116:119]
	v_mfma_f32_16x16x32_f16 v[104:107], v[158:161], v[190:193], v[104:107]
	v_mfma_f32_16x16x32_f16 v[100:103], v[166:169], v[190:193], v[100:103]
	v_mfma_f32_16x16x32_f16 v[88:91], v[158:161], v[204:207], v[88:91]
	v_mfma_f32_16x16x32_f16 v[84:87], v[166:169], v[204:207], v[84:87]
	v_mfma_f32_16x16x32_f16 v[72:75], v[158:161], v[212:215], v[72:75]
	v_mfma_f32_16x16x32_f16 v[68:71], v[166:169], v[212:215], v[68:71]
	s_barrier
	s_add_i32 s65, s86, s49
	s_mov_b32 m0, s65
	s_add_u32 s86, s6, s12
	ds_read_b128 v[170:173], v202 offset:16384
	ds_read_b128 v[174:177], v202 offset:17408
	ds_read_b128 v[178:181], v202 offset:18432
	ds_read_b128 v[190:193], v202 offset:19456
	ds_read_b128 v[198:201], v202 offset:20480
	ds_read_b128 v[204:207], v202 offset:21504
	ds_read_b128 v[208:211], v202 offset:22528
	ds_read_b128 v[212:215], v202 offset:23552
	global_load_lds_dwordx4 v32, s[6:7]
	s_addc_u32 s87, s7, s13
	s_add_i32 m0, s65, 0x2000
	v_lshl_add_u64 v[182:183], s[6:7], 0, v[32:33]
	s_add_u32 s6, s6, s8
	s_addc_u32 s7, s7, s9
	s_add_i32 s8, s45, s49
	global_load_lds_dwordx4 v32, s[86:87]
	s_mov_b32 m0, s8
	v_lshl_add_u64 v[216:217], s[6:7], 0, v[32:33]
	global_load_lds_dwordx4 v32, s[6:7]
	s_add_u32 s6, s6, s12
	s_addc_u32 s7, s7, s13
	s_add_i32 m0, s8, 0x2000
	v_lshl_add_u64 v[234:235], s[6:7], 0, v[32:33]
	global_load_lds_dwordx4 v32, s[6:7]
	s_add_u32 s6, vcc_lo, s12
	v_lshl_add_u64 v[236:237], vcc, 0, v[136:137]
	s_mov_b32 m0, s71
	s_addc_u32 s7, vcc_hi, s13
	global_load_lds_dwordx4 v[236:237], off
	v_lshl_add_u64 v[238:239], s[6:7], 0, v[136:137]
	s_mov_b32 m0, s82
	v_lshl_add_u64 v[194:195], s[86:87], 0, v[32:33]
	global_load_lds_dwordx4 v[238:239], off
	s_waitcnt vmcnt(8)
	s_waitcnt lgkmcnt(0)
	s_barrier
	v_mfma_f32_16x16x32_f16 v[64:67], v[138:141], v[170:173], v[64:67]
	v_mfma_f32_16x16x32_f16 v[60:63], v[146:149], v[170:173], v[60:63]
	v_mfma_f32_16x16x32_f16 v[48:51], v[138:141], v[178:181], v[48:51]
	v_mfma_f32_16x16x32_f16 v[44:47], v[146:149], v[178:181], v[44:47]
	v_mfma_f32_16x16x32_f16 v[28:31], v[138:141], v[198:201], v[28:31]
	v_mfma_f32_16x16x32_f16 v[24:27], v[146:149], v[198:201], v[24:27]
	v_mfma_f32_16x16x32_f16 v[12:15], v[138:141], v[208:211], v[12:15]
	v_mfma_f32_16x16x32_f16 v[8:11], v[146:149], v[208:211], v[8:11]
	v_mfma_f32_16x16x32_f16 v[64:67], v[142:145], v[174:177], v[64:67]
	v_mfma_f32_16x16x32_f16 v[60:63], v[150:153], v[174:177], v[60:63]
	v_mfma_f32_16x16x32_f16 v[48:51], v[142:145], v[190:193], v[48:51]
	v_mfma_f32_16x16x32_f16 v[44:47], v[150:153], v[190:193], v[44:47]
	v_mfma_f32_16x16x32_f16 v[28:31], v[142:145], v[204:207], v[28:31]
	v_mfma_f32_16x16x32_f16 v[24:27], v[150:153], v[204:207], v[24:27]
	v_mfma_f32_16x16x32_f16 v[12:15], v[142:145], v[212:215], v[12:15]
	v_mfma_f32_16x16x32_f16 v[8:11], v[150:153], v[212:215], v[8:11]
	v_mfma_f32_16x16x32_f16 v[56:59], v[154:157], v[170:173], v[56:59]
	v_mfma_f32_16x16x32_f16 v[52:55], v[162:165], v[170:173], v[52:55]
	v_mfma_f32_16x16x32_f16 v[40:43], v[154:157], v[178:181], v[40:43]
	v_mfma_f32_16x16x32_f16 v[36:39], v[162:165], v[178:181], v[36:39]
	v_mfma_f32_16x16x32_f16 v[20:23], v[154:157], v[198:201], v[20:23]
	v_mfma_f32_16x16x32_f16 v[16:19], v[162:165], v[198:201], v[16:19]
	v_mfma_f32_16x16x32_f16 v[4:7], v[154:157], v[208:211], v[4:7]
	v_mfma_f32_16x16x32_f16 v[0:3], v[162:165], v[208:211], v[0:3]
	v_mfma_f32_16x16x32_f16 v[56:59], v[158:161], v[174:177], v[56:59]
	v_mfma_f32_16x16x32_f16 v[52:55], v[166:169], v[174:177], v[52:55]
	v_mfma_f32_16x16x32_f16 v[40:43], v[158:161], v[190:193], v[40:43]
	v_mfma_f32_16x16x32_f16 v[36:39], v[166:169], v[190:193], v[36:39]
	v_mfma_f32_16x16x32_f16 v[20:23], v[158:161], v[204:207], v[20:23]
	v_mfma_f32_16x16x32_f16 v[16:19], v[166:169], v[204:207], v[16:19]
	v_mfma_f32_16x16x32_f16 v[4:7], v[158:161], v[212:215], v[4:7]
	v_mfma_f32_16x16x32_f16 v[0:3], v[166:169], v[212:215], v[0:3]
	s_barrier
; #define PG8_STAGE(bufoff, gbase, voff, h64) do { \
;         __builtin_amdgcn_global_load_lds((const unsigned*)((const char*)(gbase) + (voff)), (LAS unsigned*)(lds + (bufoff) + ldsw), 16, 0, 0); \
;         __builtin_amdgcn_global_load_lds((const unsigned*)((const char*)(gbase) + (h64) + (voff)), (LAS unsigned*)(lds + (bufoff) + ldsw + 8192), 16, 0, 0); } while (0)
; #define PG8_LDA(dst, b, h) do { _Pragma("unroll") for (int m = 0; m < 4; ++m) { dst[m].lo = *(const LAS f16x8*)(lds + PG8_SA(b, h) + aoff + m * 2048); dst[m].hi = *(const LAS f16x8*)(lds + PG8_SA(b, h) + aoff + m * 2048 + 1024); } } while (0)
; #define PG8_LDB(dst, b, h) do { _Pragma("unroll") for (int n = 0; n < 2; ++n) { dst[n].lo = *(const LAS f16x8*)(lds + PG8_SB(b, h) + boff + n * 2048); dst[n].hi = *(const LAS f16x8*)(lds + PG8_SB(b, h) + boff + n * 2048 + 1024); } } while (0)
; #define PG8_WAIT_V(n) asm volatile("s_waitcnt vmcnt(" #n ")" ::: "memory")
; #define PG8_WAIT_L(n) asm volatile("s_waitcnt lgkmcnt(" #n ")" ::: "memory")
; #define PG8_BAR __builtin_amdgcn_s_barrier()
; #define PG8_SCHED __builtin_amdgcn_sched_barrier(0)
; template <bool F8 = false, class Sched, class Epi>
; __device__ __forceinline__ void gemm_phase(LAS unsigned char* lds, const Sched& S, const Epi& E) {
;     ...
;         for (int t = 0; t < nt; t += 2) {
;     ...
;             PG8_LDB(B0, 1, 0); PG8_LDB(B1, 1, 1); PG8_SCHED; PG8_LDA(At, 1, 0); PG8_STAGE(PG8_SA(0, 1), a2 + hs2, vA2, h2);
;             PG8_WAIT_V(8); PG8_WAIT_L(0); PG8_BAR; PG8_MMA(0, 0, At, B0); PG8_MMA(0, 1, At, B1); PG8_BAR; PG8_SCHED;
;             PG8_LDA(At, 1, 1); PG8_STAGE(PG8_SB(1, 0), b3, vB2, h2); PG8_STAGE(PG8_SB(1, 1), b3 + bhs2, vB2, h2); PG8_STAGE(PG8_SA(1, 0), a3, vA2, h2);
;             PG8_WAIT_V(8); PG8_WAIT_L(0); PG8_BAR; PG8_MMA(1, 0, At, B0); PG8_MMA(1, 1, At, B1); PG8_BAR; PG8_SCHED;
	s_add_i32 s8, 0, 0x18000
	v_add_u32_e32 v32, s8, v187
	s_add_i32 s9, 0, 0x1c000
	ds_read_b128 v[138:141], v32
	ds_read_b128 v[142:145], v32 offset:1024
	ds_read_b128 v[146:149], v32 offset:2048
	ds_read_b128 v[150:153], v32 offset:3072
	v_add_u32_e32 v32, s9, v187
	ds_read_b128 v[154:157], v32
	ds_read_b128 v[158:161], v32 offset:1024
	ds_read_b128 v[162:165], v32 offset:2048
	ds_read_b128 v[166:169], v32 offset:3072
	s_add_u32 s6, vcc_lo, s84
	s_addc_u32 s7, vcc_hi, s85
	v_lshl_add_u64 v[240:241], s[6:7], 0, v[136:137]
	s_add_u32 s6, s6, s12
	s_mov_b32 m0, s83
	s_addc_u32 s7, s7, s13
	ds_read_b128 v[170:173], v202 offset:32768
	ds_read_b128 v[174:177], v202 offset:33792
	ds_read_b128 v[178:181], v202 offset:34816
	ds_read_b128 v[190:193], v202 offset:35840
	ds_read_b128 v[198:201], v202 offset:36864
	ds_read_b128 v[204:207], v202 offset:37888
	ds_read_b128 v[208:211], v202 offset:38912
	ds_read_b128 v[212:215], v202 offset:39936
	global_load_lds_dwordx4 v[240:241], off
	v_lshl_add_u64 v[136:137], s[6:7], 0, v[136:137]
	s_mov_b32 m0, s44
	s_nop 0
	global_load_lds_dwordx4 v[136:137], off
	s_waitcnt vmcnt(8)
	s_waitcnt lgkmcnt(0)
	s_barrier
	v_mfma_f32_16x16x32_f16 v[128:131], v[138:141], v[170:173], v[128:131]
	v_mfma_f32_16x16x32_f16 v[124:127], v[146:149], v[170:173], v[124:127]
	v_mfma_f32_16x16x32_f16 v[112:115], v[138:141], v[178:181], v[112:115]
	v_mfma_f32_16x16x32_f16 v[108:111], v[146:149], v[178:181], v[108:111]
	v_mfma_f32_16x16x32_f16 v[96:99], v[138:141], v[198:201], v[96:99]
	v_mfma_f32_16x16x32_f16 v[92:95], v[146:149], v[198:201], v[92:95]
	v_mfma_f32_16x16x32_f16 v[80:83], v[138:141], v[208:211], v[80:83]
	v_mfma_f32_16x16x32_f16 v[76:79], v[146:149], v[208:211], v[76:79]
	v_mfma_f32_16x16x32_f16 v[128:131], v[142:145], v[174:177], v[128:131]
	v_mfma_f32_16x16x32_f16 v[124:127], v[150:153], v[174:177], v[124:127]
	v_mfma_f32_16x16x32_f16 v[112:115], v[142:145], v[190:193], v[112:115]
	v_mfma_f32_16x16x32_f16 v[108:111], v[150:153], v[190:193], v[108:111]
	v_mfma_f32_16x16x32_f16 v[96:99], v[142:145], v[204:207], v[96:99]
	v_mfma_f32_16x16x32_f16 v[92:95], v[150:153], v[204:207], v[92:95]
	v_mfma_f32_16x16x32_f16 v[80:83], v[142:145], v[212:215], v[80:83]
	v_mfma_f32_16x16x32_f16 v[76:79], v[150:153], v[212:215], v[76:79]
	v_mfma_f32_16x16x32_f16 v[120:123], v[154:157], v[170:173], v[120:123]
	v_mfma_f32_16x16x32_f16 v[116:119], v[162:165], v[170:173], v[116:119]
	v_mfma_f32_16x16x32_f16 v[104:107], v[154:157], v[178:181], v[104:107]
	v_mfma_f32_16x16x32_f16 v[100:103], v[162:165], v[178:181], v[100:103]
	v_mfma_f32_16x16x32_f16 v[88:91], v[154:157], v[198:201], v[88:91]
	v_mfma_f32_16x16x32_f16 v[84:87], v[162:165], v[198:201], v[84:87]
	v_mfma_f32_16x16x32_f16 v[72:75], v[154:157], v[208:211], v[72:75]
	v_mfma_f32_16x16x32_f16 v[68:71], v[162:165], v[208:211], v[68:71]
	v_mfma_f32_16x16x32_f16 v[120:123], v[158:161], v[174:177], v[120:123]
	v_mfma_f32_16x16x32_f16 v[116:119], v[166:169], v[174:177], v[116:119]
	v_mfma_f32_16x16x32_f16 v[104:107], v[158:161], v[190:193], v[104:107]
	v_mfma_f32_16x16x32_f16 v[100:103], v[166:169], v[190:193], v[100:103]
	v_mfma_f32_16x16x32_f16 v[88:91], v[158:161], v[204:207], v[88:91]
	v_mfma_f32_16x16x32_f16 v[84:87], v[166:169], v[204:207], v[84:87]
	v_mfma_f32_16x16x32_f16 v[72:75], v[158:161], v[212:215], v[72:75]
	v_mfma_f32_16x16x32_f16 v[68:71], v[166:169], v[212:215], v[68:71]
	s_barrier
	s_add_i32 s6, s8, s49
	v_lshl_add_u64 v[136:137], v[182:183], 0, s[40:41]
	s_mov_b32 m0, s6
	ds_read_b128 v[170:173], v202 offset:49152
	ds_read_b128 v[174:177], v202 offset:50176
	ds_read_b128 v[178:181], v202 offset:51200
	ds_read_b128 v[190:193], v202 offset:52224
	ds_read_b128 v[198:201], v202 offset:53248
	ds_read_b128 v[204:207], v202 offset:54272
	ds_read_b128 v[208:211], v202 offset:55296
	ds_read_b128 v[212:215], v202 offset:56320
	global_load_lds_dwordx4 v[136:137], off
	v_lshl_add_u64 v[136:137], v[194:195], 0, s[40:41]
	s_add_i32 m0, s6, 0x2000
	s_add_i32 s6, s9, s49
	global_load_lds_dwordx4 v[136:137], off
	v_lshl_add_u64 v[136:137], v[216:217], 0, s[40:41]
	s_mov_b32 m0, s6
	s_nop 0
	global_load_lds_dwordx4 v[136:137], off
	v_lshl_add_u64 v[136:137], v[234:235], 0, s[40:41]
	s_add_i32 m0, s6, 0x2000
	s_nop 0
	global_load_lds_dwordx4 v[136:137], off
	v_lshl_add_u64 v[136:137], v[236:237], 0, s[40:41]
	s_mov_b32 m0, s92
	s_nop 0
	global_load_lds_dwordx4 v[136:137], off
	v_lshl_add_u64 v[136:137], v[238:239], 0, s[40:41]
	s_mov_b32 m0, s93
	s_nop 0
	global_load_lds_dwordx4 v[136:137], off
	s_waitcnt vmcnt(8)
	s_waitcnt lgkmcnt(0)
	s_barrier
	v_mfma_f32_16x16x32_f16 v[64:67], v[138:141], v[170:173], v[64:67]
	v_mfma_f32_16x16x32_f16 v[60:63], v[146:149], v[170:173], v[60:63]
	v_mfma_f32_16x16x32_f16 v[48:51], v[138:141], v[178:181], v[48:51]
	v_mfma_f32_16x16x32_f16 v[44:47], v[146:149], v[178:181], v[44:47]
	v_mfma_f32_16x16x32_f16 v[28:31], v[138:141], v[198:201], v[28:31]
	v_mfma_f32_16x16x32_f16 v[24:27], v[146:149], v[198:201], v[24:27]
	v_mfma_f32_16x16x32_f16 v[12:15], v[138:141], v[208:211], v[12:15]
	v_mfma_f32_16x16x32_f16 v[8:11], v[146:149], v[208:211], v[8:11]
	v_mfma_f32_16x16x32_f16 v[64:67], v[142:145], v[174:177], v[64:67]
	v_mfma_f32_16x16x32_f16 v[60:63], v[150:153], v[174:177], v[60:63]
	v_mfma_f32_16x16x32_f16 v[48:51], v[142:145], v[190:193], v[48:51]
	v_mfma_f32_16x16x32_f16 v[44:47], v[150:153], v[190:193], v[44:47]
	v_mfma_f32_16x16x32_f16 v[28:31], v[142:145], v[204:207], v[28:31]
	v_mfma_f32_16x16x32_f16 v[24:27], v[150:153], v[204:207], v[24:27]
	v_mfma_f32_16x16x32_f16 v[12:15], v[142:145], v[212:215], v[12:15]
	v_mfma_f32_16x16x32_f16 v[8:11], v[150:153], v[212:215], v[8:11]
	v_mfma_f32_16x16x32_f16 v[56:59], v[154:157], v[170:173], v[56:59]
	v_mfma_f32_16x16x32_f16 v[52:55], v[162:165], v[170:173], v[52:55]
	v_mfma_f32_16x16x32_f16 v[40:43], v[154:157], v[178:181], v[40:43]
	v_mfma_f32_16x16x32_f16 v[36:39], v[162:165], v[178:181], v[36:39]
	v_mfma_f32_16x16x32_f16 v[20:23], v[154:157], v[198:201], v[20:23]
	v_mfma_f32_16x16x32_f16 v[16:19], v[162:165], v[198:201], v[16:19]
	v_mfma_f32_16x16x32_f16 v[4:7], v[154:157], v[208:211], v[4:7]
	v_mfma_f32_16x16x32_f16 v[0:3], v[162:165], v[208:211], v[0:3]
	v_mfma_f32_16x16x32_f16 v[56:59], v[158:161], v[174:177], v[56:59]
	v_mfma_f32_16x16x32_f16 v[52:55], v[166:169], v[174:177], v[52:55]
	v_mfma_f32_16x16x32_f16 v[40:43], v[158:161], v[190:193], v[40:43]
	v_mfma_f32_16x16x32_f16 v[36:39], v[166:169], v[190:193], v[36:39]
	v_mfma_f32_16x16x32_f16 v[20:23], v[158:161], v[204:207], v[20:23]
	v_mfma_f32_16x16x32_f16 v[16:19], v[166:169], v[204:207], v[16:19]
	v_mfma_f32_16x16x32_f16 v[4:7], v[158:161], v[212:215], v[4:7]
	v_mfma_f32_16x16x32_f16 v[0:3], v[166:169], v[212:215], v[0:3]
	s_barrier
	s_add_u32 s10, s10, 0x100
	s_addc_u32 s11, s11, 0
	s_cmp_ge_u32 s79, s36
	s_cbranch_scc1 .LBB0_217
